# MLA items: row_scales loads issued together (q-up loop unrolled into v[24:87], kv-up two groups merged) with counted waits
# baseline (speedup 1.0000x reference)
; #define BLO(u) __uint_as_float((u) << 16)
; #define BHI(u) __uint_as_float((u) & 0xffff0000u)
; DI int otid() { int t; asm volatile("v_mov_b32 %0, %1" : "=v"(t) : "v"((int)threadIdx.x)); __builtin_assume(t >= 0 && t < 256); return t; }
; DI void row_scales(const bf16_t* A, int lda, int K, float* sRow) {
;   const int row = otid() >> 1, half = otid() & 1;
;   const int per = K >> 1;
;   const bf16_t* a = A + (size_t)row * lda + half * per;
;   float ss = 0.f;
;   for (int c = 0; c < per; c += 8) {
;     uint4 u = *(const uint4*)(a + c);
;     float f;
;     f = BLO(u.x); ss += f * f; f = BHI(u.x); ss += f * f; f = BLO(u.y); ss += f * f; f = BHI(u.y); ss += f * f;
;     f = BLO(u.z); ss += f * f; f = BHI(u.z); ss += f * f; f = BLO(u.w); ss += f * f; f = BHI(u.w); ss += f * f;
;   }
;   ss += __shfl_xor(ss, 1);
;   if (half == 0) sRow[row] = rsqrtf(ss / (float)K + 1e-6f);
; }
; DI void mla_item(const Params& p, int l, int item, char* smem) {
;     ...
;     row_scales(A, PW, 128, sRow);
.LBB0_217:
	s_and_b64 vcc, exec, s[0:1]
	s_cbranch_vccz .LBB0_230
	s_lshl_b32 s0, s27, 7
	s_and_b32 s6, s0, 0x7f80
	s_mul_i32 s0, s6, 0x2600
	s_add_u32 s0, s58, s0
	s_addc_u32 s1, s59, 0
	s_barrier
	v_mov_b32 v0, v188
	s_add_u32 s0, s0, 0x6ca6400
	v_lshrrev_b32_e32 v16, 1, v0
	v_mov_b32 v0, v188
	s_addc_u32 s1, s1, 0
	v_and_b32_e32 v17, 1, v0
	v_mul_u32_u24_e32 v0, 0x2600, v16
	v_lshl_add_u64 v[2:3], s[0:1], 0, v[0:1]
	v_lshlrev_b32_e32 v0, 7, v17
	v_lshl_add_u64 v[14:15], v[2:3], 0, v[0:1]
	global_load_dwordx4 v[2:5], v[14:15], off offset:48
	global_load_dwordx4 v[6:9], v[14:15], off offset:32
	global_load_dwordx4 v[10:13], v[14:15], off offset:16
	global_load_dwordx4 v[18:21], v[14:15], off
	global_load_dwordx4 v[24:27], v[14:15], off offset:112
	global_load_dwordx4 v[28:31], v[14:15], off offset:96
	global_load_dwordx4 v[32:35], v[14:15], off offset:80
	global_load_dwordx4 v[36:39], v[14:15], off offset:64
	v_cmp_lt_i32_e32 vcc, v195, v189
	s_waitcnt vmcnt(4)
	v_lshlrev_b32_e32 v0, 16, v18
	v_mul_f32_e32 v0, v0, v0
	v_and_b32_e32 v18, 0xffff0000, v18
	v_fmac_f32_e32 v0, v18, v18
	v_lshlrev_b32_e32 v18, 16, v19
	v_fmac_f32_e32 v0, v18, v18
	v_and_b32_e32 v18, 0xffff0000, v19
	v_fmac_f32_e32 v0, v18, v18
	v_lshlrev_b32_e32 v18, 16, v20
	v_fmac_f32_e32 v0, v18, v18
	v_and_b32_e32 v18, 0xffff0000, v20
	v_fmac_f32_e32 v0, v18, v18
	v_lshlrev_b32_e32 v18, 16, v21
	v_fmac_f32_e32 v0, v18, v18
	v_and_b32_e32 v18, 0xffff0000, v21
	v_fmac_f32_e32 v0, v18, v18
	v_lshlrev_b32_e32 v18, 16, v10
	v_fmac_f32_e32 v0, v18, v18
	v_and_b32_e32 v10, 0xffff0000, v10
	v_fmac_f32_e32 v0, v10, v10
	v_lshlrev_b32_e32 v10, 16, v11
	v_fmac_f32_e32 v0, v10, v10
	v_and_b32_e32 v10, 0xffff0000, v11
	v_fmac_f32_e32 v0, v10, v10
	v_lshlrev_b32_e32 v10, 16, v12
	v_fmac_f32_e32 v0, v10, v10
	v_and_b32_e32 v10, 0xffff0000, v12
	v_fmac_f32_e32 v0, v10, v10
	v_lshlrev_b32_e32 v10, 16, v13
	v_fmac_f32_e32 v0, v10, v10
	v_and_b32_e32 v10, 0xffff0000, v13
	v_fmac_f32_e32 v0, v10, v10
	v_lshlrev_b32_e32 v10, 16, v6
	v_fmac_f32_e32 v0, v10, v10
	v_and_b32_e32 v6, 0xffff0000, v6
	v_fmac_f32_e32 v0, v6, v6
	v_lshlrev_b32_e32 v6, 16, v7
	v_fmac_f32_e32 v0, v6, v6
	v_and_b32_e32 v6, 0xffff0000, v7
	v_fmac_f32_e32 v0, v6, v6
	v_lshlrev_b32_e32 v6, 16, v8
	v_fmac_f32_e32 v0, v6, v6
	v_and_b32_e32 v6, 0xffff0000, v8
	v_fmac_f32_e32 v0, v6, v6
	v_lshlrev_b32_e32 v6, 16, v9
	v_fmac_f32_e32 v0, v6, v6
	v_and_b32_e32 v6, 0xffff0000, v9
	v_fmac_f32_e32 v0, v6, v6
	v_lshlrev_b32_e32 v6, 16, v2
	v_fmac_f32_e32 v0, v6, v6
	v_and_b32_e32 v2, 0xffff0000, v2
	v_fmac_f32_e32 v0, v2, v2
	v_lshlrev_b32_e32 v2, 16, v3
	v_fmac_f32_e32 v0, v2, v2
	v_and_b32_e32 v2, 0xffff0000, v3
	v_fmac_f32_e32 v0, v2, v2
	v_lshlrev_b32_e32 v2, 16, v4
	v_fmac_f32_e32 v0, v2, v2
	v_and_b32_e32 v2, 0xffff0000, v4
	v_fmac_f32_e32 v0, v2, v2
	v_lshlrev_b32_e32 v2, 16, v5
	v_fmac_f32_e32 v0, v2, v2
	v_and_b32_e32 v2, 0xffff0000, v5
	v_fmac_f32_e32 v0, v2, v2
	s_waitcnt vmcnt(0)
	v_lshlrev_b32_e32 v14, 16, v36
	v_fmac_f32_e32 v0, v14, v14
	v_and_b32_e32 v14, 0xffff0000, v36
	v_fmac_f32_e32 v0, v14, v14
	v_lshlrev_b32_e32 v14, 16, v37
	v_fmac_f32_e32 v0, v14, v14
	v_and_b32_e32 v14, 0xffff0000, v37
	v_fmac_f32_e32 v0, v14, v14
	v_lshlrev_b32_e32 v14, 16, v38
	v_fmac_f32_e32 v0, v14, v14
	v_and_b32_e32 v14, 0xffff0000, v38
	v_fmac_f32_e32 v0, v14, v14
	v_lshlrev_b32_e32 v14, 16, v39
	v_fmac_f32_e32 v0, v14, v14
	v_and_b32_e32 v14, 0xffff0000, v39
	v_fmac_f32_e32 v0, v14, v14
	v_lshlrev_b32_e32 v14, 16, v32
	v_fmac_f32_e32 v0, v14, v14
	v_and_b32_e32 v32, 0xffff0000, v32
	v_fmac_f32_e32 v0, v32, v32
	v_lshlrev_b32_e32 v32, 16, v33
	v_fmac_f32_e32 v0, v32, v32
	v_and_b32_e32 v32, 0xffff0000, v33
	v_fmac_f32_e32 v0, v32, v32
	v_lshlrev_b32_e32 v32, 16, v34
	v_fmac_f32_e32 v0, v32, v32
	v_and_b32_e32 v32, 0xffff0000, v34
	v_fmac_f32_e32 v0, v32, v32
	v_lshlrev_b32_e32 v32, 16, v35
	v_fmac_f32_e32 v0, v32, v32
	v_and_b32_e32 v32, 0xffff0000, v35
	v_fmac_f32_e32 v0, v32, v32
	v_lshlrev_b32_e32 v32, 16, v28
	v_fmac_f32_e32 v0, v32, v32
	v_and_b32_e32 v28, 0xffff0000, v28
	v_fmac_f32_e32 v0, v28, v28
	v_lshlrev_b32_e32 v28, 16, v29
	v_fmac_f32_e32 v0, v28, v28
	v_and_b32_e32 v28, 0xffff0000, v29
	v_fmac_f32_e32 v0, v28, v28
	v_lshlrev_b32_e32 v28, 16, v30
	v_fmac_f32_e32 v0, v28, v28
	v_and_b32_e32 v28, 0xffff0000, v30
	v_fmac_f32_e32 v0, v28, v28
	v_lshlrev_b32_e32 v28, 16, v31
	v_fmac_f32_e32 v0, v28, v28
	v_and_b32_e32 v28, 0xffff0000, v31
	v_fmac_f32_e32 v0, v28, v28
	v_lshlrev_b32_e32 v28, 16, v24
	v_fmac_f32_e32 v0, v28, v28
	v_and_b32_e32 v24, 0xffff0000, v24
	v_fmac_f32_e32 v0, v24, v24
	v_lshlrev_b32_e32 v24, 16, v25
	v_fmac_f32_e32 v0, v24, v24
	v_and_b32_e32 v24, 0xffff0000, v25
	v_fmac_f32_e32 v0, v24, v24
	v_lshlrev_b32_e32 v24, 16, v26
	v_fmac_f32_e32 v0, v24, v24
	v_and_b32_e32 v24, 0xffff0000, v26
	v_fmac_f32_e32 v0, v24, v24
	v_lshlrev_b32_e32 v24, 16, v27
	v_fmac_f32_e32 v0, v24, v24
	v_and_b32_e32 v24, 0xffff0000, v27
	v_fmac_f32_e32 v0, v24, v24
	v_cndmask_b32_e32 v24, v204, v195, vcc
	v_lshlrev_b32_e32 v24, 2, v24
	ds_bpermute_b32 v24, v24, v0
	v_cmp_eq_u32_e32 vcc, 0, v17
	s_and_saveexec_b64 s[22:23], vcc
	s_cbranch_execz .LBB0_220
	s_waitcnt lgkmcnt(0)
	v_add_f32_e32 v0, v0, v24
	v_fmamk_f32 v0, v0, 0x3c000000, v190
	v_mul_f32_e32 v24, 0x4b800000, v0
	v_cmp_gt_f32_e32 vcc, s3, v0
	s_nop 1
	v_cndmask_b32_e32 v0, v0, v24, vcc
	v_rsq_f32_e32 v0, v0
	s_nop 0
	v_mul_f32_e32 v24, 0x45800000, v0
	v_cndmask_b32_e32 v0, v0, v24, vcc
	v_mov_b32_e32 v24, 0x10000
	v_lshl_add_u32 v24, v16, 2, v24
	ds_write_b32 v24, v0

; #define BLO(u) __uint_as_float((u) << 16)
; #define BHI(u) __uint_as_float((u) & 0xffff0000u)
; DI int otid() { int t; asm volatile("v_mov_b32 %0, %1" : "=v"(t) : "v"((int)threadIdx.x)); __builtin_assume(t >= 0 && t < 256); return t; }
; DI void row_scales(const bf16_t* A, int lda, int K, float* sRow) {
;   const int row = otid() >> 1, half = otid() & 1;
;   const int per = K >> 1;
;   const bf16_t* a = A + (size_t)row * lda + half * per;
;   float ss = 0.f;
;   for (int c = 0; c < per; c += 8) {
;     uint4 u = *(const uint4*)(a + c);
;     float f;
;     f = BLO(u.x); ss += f * f; f = BHI(u.x); ss += f * f; f = BLO(u.y); ss += f * f; f = BHI(u.y); ss += f * f;
;     f = BLO(u.z); ss += f * f; f = BHI(u.z); ss += f * f; f = BLO(u.w); ss += f * f; f = BHI(u.w); ss += f * f;
;   }
;   ss += __shfl_xor(ss, 1);
;   if (half == 0) sRow[row] = rsqrtf(ss / (float)K + 1e-6f);
; }
; DI void mla_item(const Params& p, int l, int item, char* smem) {
;     ...
;     row_scales(A, PW, 256, sRow);
.LBB0_222:
	s_bfe_u32 s0, s26, 0x80007
	s_mul_i32 s0, s0, 0x130000
	s_barrier
	v_mov_b32 v0, v188
	v_mov_b32 v2, v188
	v_mov_b32_e32 v3, v1
	v_lshrrev_b32_e32 v4, 1, v0
	v_and_b32_e32 v5, 1, v2
	v_mul_u32_u24_e32 v0, 0x2600, v4
	v_lshl_or_b32 v2, v5, 8, s0
	v_readlane_b32 s0, v255, 20
	v_lshl_add_u64 v[2:3], v[2:3], 0, v[0:1]
	v_readlane_b32 s1, v255, 21
	v_mov_b32_e32 v0, 0
	s_nop 0
	v_lshl_add_u64 v[2:3], s[0:1], 0, v[2:3]
	s_mov_b32 s0, -8
	global_load_dwordx4 v[24:27], v[2:3], off offset:16
	global_load_dwordx4 v[28:31], v[2:3], off
	global_load_dwordx4 v[32:35], v[2:3], off offset:-16
	global_load_dwordx4 v[36:39], v[2:3], off offset:-32
	global_load_dwordx4 v[40:43], v[2:3], off offset:80
	global_load_dwordx4 v[44:47], v[2:3], off offset:64
	global_load_dwordx4 v[48:51], v[2:3], off offset:48
	global_load_dwordx4 v[52:55], v[2:3], off offset:32
	global_load_dwordx4 v[56:59], v[2:3], off offset:144
	global_load_dwordx4 v[60:63], v[2:3], off offset:128
	global_load_dwordx4 v[64:67], v[2:3], off offset:112
	global_load_dwordx4 v[68:71], v[2:3], off offset:96
	global_load_dwordx4 v[72:75], v[2:3], off offset:208
	global_load_dwordx4 v[76:79], v[2:3], off offset:192
	global_load_dwordx4 v[80:83], v[2:3], off offset:176
	global_load_dwordx4 v[84:87], v[2:3], off offset:160
.LBB0_223:
	s_waitcnt vmcnt(12)
	v_lshlrev_b32_e32 v22, 16, v36
	v_fmac_f32_e32 v0, v22, v22
	v_lshlrev_b32_e32 v23, 16, v37
	v_and_b32_e32 v22, 0xffff0000, v36
	v_mul_f32_e32 v22, v22, v22
	v_mul_f32_e32 v23, v23, v23
	v_lshlrev_b32_e32 v36, 16, v38
	v_add_f32_e32 v0, v22, v0
	v_and_b32_e32 v37, 0xffff0000, v37
	v_add_f32_e32 v0, v23, v0
	v_mul_f32_e32 v36, v36, v36
	v_mul_f32_e32 v37, v37, v37
	s_nop 0
	v_add_f32_e32 v0, v37, v0
	v_add_f32_e32 v0, v36, v0
	v_lshlrev_b32_e32 v37, 16, v39
	v_and_b32_e32 v36, 0xffff0000, v38
	v_mul_f32_e32 v36, v36, v36
	v_mul_f32_e32 v37, v37, v37
	s_nop 0
	v_add_f32_e32 v0, v36, v0
	v_add_f32_e32 v0, v37, v0
	v_and_b32_e32 v36, 0xffff0000, v39
	v_fmac_f32_e32 v0, v36, v36
	v_lshlrev_b32_e32 v36, 16, v32
	v_fmac_f32_e32 v0, v36, v36
	v_lshlrev_b32_e32 v37, 16, v33
	v_and_b32_e32 v36, 0xffff0000, v32
	v_mul_f32_e32 v36, v36, v36
	v_mul_f32_e32 v37, v37, v37
	v_lshlrev_b32_e32 v32, 16, v34
	v_add_f32_e32 v0, v36, v0
	v_and_b32_e32 v33, 0xffff0000, v33
	v_add_f32_e32 v0, v37, v0
	v_mul_f32_e32 v32, v32, v32
	v_mul_f32_e32 v33, v33, v33
	s_nop 0
	v_add_f32_e32 v0, v33, v0
	v_add_f32_e32 v0, v32, v0
	v_lshlrev_b32_e32 v33, 16, v35
	v_and_b32_e32 v32, 0xffff0000, v34
	v_mul_f32_e32 v32, v32, v32
	v_mul_f32_e32 v33, v33, v33
	s_nop 0
	v_add_f32_e32 v0, v32, v0
	v_add_f32_e32 v0, v33, v0
	v_and_b32_e32 v32, 0xffff0000, v35
	v_fmac_f32_e32 v0, v32, v32
	v_lshlrev_b32_e32 v32, 16, v28
	v_fmac_f32_e32 v0, v32, v32
	v_lshlrev_b32_e32 v33, 16, v29
	v_and_b32_e32 v32, 0xffff0000, v28
	v_mul_f32_e32 v32, v32, v32
	v_mul_f32_e32 v33, v33, v33
	v_lshlrev_b32_e32 v28, 16, v30
	v_add_f32_e32 v0, v32, v0
	v_and_b32_e32 v29, 0xffff0000, v29
	v_add_f32_e32 v0, v33, v0
	v_mul_f32_e32 v28, v28, v28
	v_mul_f32_e32 v29, v29, v29
	s_nop 0
	v_add_f32_e32 v0, v29, v0
	v_add_f32_e32 v0, v28, v0
	v_lshlrev_b32_e32 v29, 16, v31
	v_and_b32_e32 v28, 0xffff0000, v30
	v_mul_f32_e32 v28, v28, v28
	v_mul_f32_e32 v29, v29, v29
	s_nop 0
	v_add_f32_e32 v0, v28, v0
	v_add_f32_e32 v0, v29, v0
	v_and_b32_e32 v28, 0xffff0000, v31
	v_fmac_f32_e32 v0, v28, v28
	v_lshlrev_b32_e32 v28, 16, v24
	v_fmac_f32_e32 v0, v28, v28
	v_lshlrev_b32_e32 v29, 16, v25
	v_and_b32_e32 v28, 0xffff0000, v24
	v_mul_f32_e32 v28, v28, v28
	v_mul_f32_e32 v29, v29, v29
	v_lshlrev_b32_e32 v24, 16, v26
	v_add_f32_e32 v0, v28, v0
	v_and_b32_e32 v25, 0xffff0000, v25
	v_add_f32_e32 v0, v29, v0
	v_mul_f32_e32 v24, v24, v24
	v_mul_f32_e32 v25, v25, v25
	s_nop 0
	v_add_f32_e32 v0, v25, v0
	v_add_f32_e32 v0, v24, v0
	v_lshlrev_b32_e32 v25, 16, v27
	v_and_b32_e32 v24, 0xffff0000, v26
	v_mul_f32_e32 v24, v24, v24
	v_mul_f32_e32 v25, v25, v25
	s_nop 0
	v_add_f32_e32 v0, v24, v0
	v_add_f32_e32 v0, v25, v0
	v_and_b32_e32 v24, 0xffff0000, v27
	v_fmac_f32_e32 v0, v24, v24
	s_waitcnt vmcnt(8)
	v_lshlrev_b32_e32 v22, 16, v52
	v_fmac_f32_e32 v0, v22, v22
	v_lshlrev_b32_e32 v23, 16, v53
	v_and_b32_e32 v22, 0xffff0000, v52
	v_mul_f32_e32 v22, v22, v22
	v_mul_f32_e32 v23, v23, v23
	v_lshlrev_b32_e32 v52, 16, v54
	v_add_f32_e32 v0, v22, v0
	v_and_b32_e32 v53, 0xffff0000, v53
	v_add_f32_e32 v0, v23, v0
	v_mul_f32_e32 v52, v52, v52
	v_mul_f32_e32 v53, v53, v53
	s_nop 0
	v_add_f32_e32 v0, v53, v0
	v_add_f32_e32 v0, v52, v0
	v_lshlrev_b32_e32 v53, 16, v55
	v_and_b32_e32 v52, 0xffff0000, v54
	v_mul_f32_e32 v52, v52, v52
	v_mul_f32_e32 v53, v53, v53
	s_nop 0
	v_add_f32_e32 v0, v52, v0
	v_add_f32_e32 v0, v53, v0
	v_and_b32_e32 v52, 0xffff0000, v55
	v_fmac_f32_e32 v0, v52, v52
	v_lshlrev_b32_e32 v52, 16, v48
	v_fmac_f32_e32 v0, v52, v52
	v_lshlrev_b32_e32 v53, 16, v49
	v_and_b32_e32 v52, 0xffff0000, v48
	v_mul_f32_e32 v52, v52, v52
	v_mul_f32_e32 v53, v53, v53
	v_lshlrev_b32_e32 v48, 16, v50
	v_add_f32_e32 v0, v52, v0
	v_and_b32_e32 v49, 0xffff0000, v49
	v_add_f32_e32 v0, v53, v0
	v_mul_f32_e32 v48, v48, v48
	v_mul_f32_e32 v49, v49, v49
	s_nop 0
	v_add_f32_e32 v0, v49, v0
	v_add_f32_e32 v0, v48, v0
	v_lshlrev_b32_e32 v49, 16, v51
	v_and_b32_e32 v48, 0xffff0000, v50
	v_mul_f32_e32 v48, v48, v48
	v_mul_f32_e32 v49, v49, v49
	s_nop 0
	v_add_f32_e32 v0, v48, v0
	v_add_f32_e32 v0, v49, v0
	v_and_b32_e32 v48, 0xffff0000, v51
	v_fmac_f32_e32 v0, v48, v48
	v_lshlrev_b32_e32 v48, 16, v44
	v_fmac_f32_e32 v0, v48, v48
	v_lshlrev_b32_e32 v49, 16, v45
	v_and_b32_e32 v48, 0xffff0000, v44
	v_mul_f32_e32 v48, v48, v48
	v_mul_f32_e32 v49, v49, v49
	v_lshlrev_b32_e32 v44, 16, v46
	v_add_f32_e32 v0, v48, v0
	v_and_b32_e32 v45, 0xffff0000, v45
	v_add_f32_e32 v0, v49, v0
	v_mul_f32_e32 v44, v44, v44
	v_mul_f32_e32 v45, v45, v45
	s_nop 0
	v_add_f32_e32 v0, v45, v0
	v_add_f32_e32 v0, v44, v0
	v_lshlrev_b32_e32 v45, 16, v47
	v_and_b32_e32 v44, 0xffff0000, v46
	v_mul_f32_e32 v44, v44, v44
	v_mul_f32_e32 v45, v45, v45
	s_nop 0
	v_add_f32_e32 v0, v44, v0
	v_add_f32_e32 v0, v45, v0
	v_and_b32_e32 v44, 0xffff0000, v47
	v_fmac_f32_e32 v0, v44, v44
	v_lshlrev_b32_e32 v44, 16, v40
	v_fmac_f32_e32 v0, v44, v44
	v_lshlrev_b32_e32 v45, 16, v41
	v_and_b32_e32 v44, 0xffff0000, v40
	v_mul_f32_e32 v44, v44, v44
	v_mul_f32_e32 v45, v45, v45
	v_lshlrev_b32_e32 v40, 16, v42
	v_add_f32_e32 v0, v44, v0
	v_and_b32_e32 v41, 0xffff0000, v41
	v_add_f32_e32 v0, v45, v0
	v_mul_f32_e32 v40, v40, v40
	v_mul_f32_e32 v41, v41, v41
	s_nop 0
	v_add_f32_e32 v0, v41, v0
	v_add_f32_e32 v0, v40, v0
	v_lshlrev_b32_e32 v41, 16, v43
	v_and_b32_e32 v40, 0xffff0000, v42
	v_mul_f32_e32 v40, v40, v40
	v_mul_f32_e32 v41, v41, v41
	s_nop 0
	v_add_f32_e32 v0, v40, v0
	v_add_f32_e32 v0, v41, v0
	v_and_b32_e32 v40, 0xffff0000, v43
	v_fmac_f32_e32 v0, v40, v40
	s_waitcnt vmcnt(4)
; #define BLO(u) __uint_as_float((u) << 16)
; #define BHI(u) __uint_as_float((u) & 0xffff0000u)
; DI int otid() { int t; asm volatile("v_mov_b32 %0, %1" : "=v"(t) : "v"((int)threadIdx.x)); __builtin_assume(t >= 0 && t < 256); return t; }
; DI void row_scales(const bf16_t* A, int lda, int K, float* sRow) {
;   const int row = otid() >> 1, half = otid() & 1;
;   const int per = K >> 1;
;   const bf16_t* a = A + (size_t)row * lda + half * per;
;   float ss = 0.f;
;   for (int c = 0; c < per; c += 8) {
;     uint4 u = *(const uint4*)(a + c);
;     float f;
;     f = BLO(u.x); ss += f * f; f = BHI(u.x); ss += f * f; f = BLO(u.y); ss += f * f; f = BHI(u.y); ss += f * f;
;     f = BLO(u.z); ss += f * f; f = BHI(u.z); ss += f * f; f = BLO(u.w); ss += f * f; f = BHI(u.w); ss += f * f;
;   }
;   ss += __shfl_xor(ss, 1);
;   if (half == 0) sRow[row] = rsqrtf(ss / (float)K + 1e-6f);
; }
; DI void mla_item(const Params& p, int l, int item, char* smem) {
;     ...
;     row_scales(A, PW, 256, sRow);
	v_lshlrev_b32_e32 v22, 16, v68
	v_fmac_f32_e32 v0, v22, v22
	v_lshlrev_b32_e32 v23, 16, v69
	v_and_b32_e32 v22, 0xffff0000, v68
	v_mul_f32_e32 v22, v22, v22
	v_mul_f32_e32 v23, v23, v23
	v_lshlrev_b32_e32 v68, 16, v70
	v_add_f32_e32 v0, v22, v0
	v_and_b32_e32 v69, 0xffff0000, v69
	v_add_f32_e32 v0, v23, v0
	v_mul_f32_e32 v68, v68, v68
	v_mul_f32_e32 v69, v69, v69
	s_nop 0
	v_add_f32_e32 v0, v69, v0
	v_add_f32_e32 v0, v68, v0
	v_lshlrev_b32_e32 v69, 16, v71
	v_and_b32_e32 v68, 0xffff0000, v70
	v_mul_f32_e32 v68, v68, v68
	v_mul_f32_e32 v69, v69, v69
	s_nop 0
	v_add_f32_e32 v0, v68, v0
	v_add_f32_e32 v0, v69, v0
	v_and_b32_e32 v68, 0xffff0000, v71
	v_fmac_f32_e32 v0, v68, v68
	v_lshlrev_b32_e32 v68, 16, v64
	v_fmac_f32_e32 v0, v68, v68
	v_lshlrev_b32_e32 v69, 16, v65
	v_and_b32_e32 v68, 0xffff0000, v64
	v_mul_f32_e32 v68, v68, v68
	v_mul_f32_e32 v69, v69, v69
	v_lshlrev_b32_e32 v64, 16, v66
	v_add_f32_e32 v0, v68, v0
	v_and_b32_e32 v65, 0xffff0000, v65
	v_add_f32_e32 v0, v69, v0
	v_mul_f32_e32 v64, v64, v64
	v_mul_f32_e32 v65, v65, v65
	s_nop 0
	v_add_f32_e32 v0, v65, v0
	v_add_f32_e32 v0, v64, v0
	v_lshlrev_b32_e32 v65, 16, v67
	v_and_b32_e32 v64, 0xffff0000, v66
	v_mul_f32_e32 v64, v64, v64
	v_mul_f32_e32 v65, v65, v65
	s_nop 0
	v_add_f32_e32 v0, v64, v0
	v_add_f32_e32 v0, v65, v0
	v_and_b32_e32 v64, 0xffff0000, v67
	v_fmac_f32_e32 v0, v64, v64
	v_lshlrev_b32_e32 v64, 16, v60
	v_fmac_f32_e32 v0, v64, v64
	v_lshlrev_b32_e32 v65, 16, v61
	v_and_b32_e32 v64, 0xffff0000, v60
	v_mul_f32_e32 v64, v64, v64
	v_mul_f32_e32 v65, v65, v65
	v_lshlrev_b32_e32 v60, 16, v62
	v_add_f32_e32 v0, v64, v0
	v_and_b32_e32 v61, 0xffff0000, v61
	v_add_f32_e32 v0, v65, v0
	v_mul_f32_e32 v60, v60, v60
	v_mul_f32_e32 v61, v61, v61
	s_nop 0
	v_add_f32_e32 v0, v61, v0
	v_add_f32_e32 v0, v60, v0
	v_lshlrev_b32_e32 v61, 16, v63
	v_and_b32_e32 v60, 0xffff0000, v62
	v_mul_f32_e32 v60, v60, v60
	v_mul_f32_e32 v61, v61, v61
	s_nop 0
	v_add_f32_e32 v0, v60, v0
	v_add_f32_e32 v0, v61, v0
	v_and_b32_e32 v60, 0xffff0000, v63
	v_fmac_f32_e32 v0, v60, v60
	v_lshlrev_b32_e32 v60, 16, v56
	v_fmac_f32_e32 v0, v60, v60
	v_lshlrev_b32_e32 v61, 16, v57
	v_and_b32_e32 v60, 0xffff0000, v56
	v_mul_f32_e32 v60, v60, v60
	v_mul_f32_e32 v61, v61, v61
	v_lshlrev_b32_e32 v56, 16, v58
	v_add_f32_e32 v0, v60, v0
	v_and_b32_e32 v57, 0xffff0000, v57
	v_add_f32_e32 v0, v61, v0
	v_mul_f32_e32 v56, v56, v56
	v_mul_f32_e32 v57, v57, v57
	s_nop 0
	v_add_f32_e32 v0, v57, v0
	v_add_f32_e32 v0, v56, v0
	v_lshlrev_b32_e32 v57, 16, v59
	v_and_b32_e32 v56, 0xffff0000, v58
	v_mul_f32_e32 v56, v56, v56
	v_mul_f32_e32 v57, v57, v57
	s_nop 0
	v_add_f32_e32 v0, v56, v0
	v_add_f32_e32 v0, v57, v0
	v_and_b32_e32 v56, 0xffff0000, v59
	v_fmac_f32_e32 v0, v56, v56
	s_waitcnt vmcnt(0)
	v_lshlrev_b32_e32 v22, 16, v84
	v_fmac_f32_e32 v0, v22, v22
	v_lshlrev_b32_e32 v23, 16, v85
	v_and_b32_e32 v22, 0xffff0000, v84
	v_mul_f32_e32 v22, v22, v22
	v_mul_f32_e32 v23, v23, v23
	v_lshlrev_b32_e32 v84, 16, v86
	v_add_f32_e32 v0, v22, v0
	v_and_b32_e32 v85, 0xffff0000, v85
	v_add_f32_e32 v0, v23, v0
	v_mul_f32_e32 v84, v84, v84
	v_mul_f32_e32 v85, v85, v85
	s_nop 0
	v_add_f32_e32 v0, v85, v0
	v_add_f32_e32 v0, v84, v0
	v_lshlrev_b32_e32 v85, 16, v87
	v_and_b32_e32 v84, 0xffff0000, v86
	v_mul_f32_e32 v84, v84, v84
	v_mul_f32_e32 v85, v85, v85
	s_nop 0
	v_add_f32_e32 v0, v84, v0
	v_add_f32_e32 v0, v85, v0
	v_and_b32_e32 v84, 0xffff0000, v87
	v_fmac_f32_e32 v0, v84, v84
	v_lshlrev_b32_e32 v84, 16, v80
	v_fmac_f32_e32 v0, v84, v84
	v_lshlrev_b32_e32 v85, 16, v81
	v_and_b32_e32 v84, 0xffff0000, v80
	v_mul_f32_e32 v84, v84, v84
	v_mul_f32_e32 v85, v85, v85
	v_lshlrev_b32_e32 v80, 16, v82
	v_add_f32_e32 v0, v84, v0
	v_and_b32_e32 v81, 0xffff0000, v81
	v_add_f32_e32 v0, v85, v0
	v_mul_f32_e32 v80, v80, v80
	v_mul_f32_e32 v81, v81, v81
	s_nop 0
	v_add_f32_e32 v0, v81, v0
	v_add_f32_e32 v0, v80, v0
	v_lshlrev_b32_e32 v81, 16, v83
	v_and_b32_e32 v80, 0xffff0000, v82
	v_mul_f32_e32 v80, v80, v80
	v_mul_f32_e32 v81, v81, v81
	s_nop 0
	v_add_f32_e32 v0, v80, v0
	v_add_f32_e32 v0, v81, v0
	v_and_b32_e32 v80, 0xffff0000, v83
	v_fmac_f32_e32 v0, v80, v80
	v_lshlrev_b32_e32 v80, 16, v76
	v_fmac_f32_e32 v0, v80, v80
	v_lshlrev_b32_e32 v81, 16, v77
	v_and_b32_e32 v80, 0xffff0000, v76
	v_mul_f32_e32 v80, v80, v80
	v_mul_f32_e32 v81, v81, v81
	v_lshlrev_b32_e32 v76, 16, v78
	v_add_f32_e32 v0, v80, v0
	v_and_b32_e32 v77, 0xffff0000, v77
	v_add_f32_e32 v0, v81, v0
	v_mul_f32_e32 v76, v76, v76
	v_mul_f32_e32 v77, v77, v77
	s_nop 0
	v_add_f32_e32 v0, v77, v0
	v_add_f32_e32 v0, v76, v0
	v_lshlrev_b32_e32 v77, 16, v79
	v_and_b32_e32 v76, 0xffff0000, v78
	v_mul_f32_e32 v76, v76, v76
	v_mul_f32_e32 v77, v77, v77
	s_nop 0
	v_add_f32_e32 v0, v76, v0
	v_add_f32_e32 v0, v77, v0
	v_and_b32_e32 v76, 0xffff0000, v79
	v_fmac_f32_e32 v0, v76, v76
	v_lshlrev_b32_e32 v76, 16, v72
	v_fmac_f32_e32 v0, v76, v76
	v_lshlrev_b32_e32 v77, 16, v73
	v_and_b32_e32 v76, 0xffff0000, v72
	v_mul_f32_e32 v76, v76, v76
	v_mul_f32_e32 v77, v77, v77
	v_lshlrev_b32_e32 v72, 16, v74
	v_add_f32_e32 v0, v76, v0
	v_and_b32_e32 v73, 0xffff0000, v73
	v_add_f32_e32 v0, v77, v0
	v_mul_f32_e32 v72, v72, v72
	v_mul_f32_e32 v73, v73, v73
	s_nop 0
	v_add_f32_e32 v0, v73, v0
	v_add_f32_e32 v0, v72, v0
	v_lshlrev_b32_e32 v73, 16, v75
	v_and_b32_e32 v72, 0xffff0000, v74
	v_mul_f32_e32 v72, v72, v72
	v_mul_f32_e32 v73, v73, v73
	s_nop 0
	v_add_f32_e32 v0, v72, v0
	v_add_f32_e32 v0, v73, v0
	v_and_b32_e32 v72, 0xffff0000, v75
	v_fmac_f32_e32 v0, v72, v72
	v_cmp_lt_i32_e32 vcc, v195, v189
	s_nop 1
	v_cndmask_b32_e32 v2, v204, v195, vcc
	v_lshlrev_b32_e32 v2, 2, v2
	ds_bpermute_b32 v2, v2, v0
	v_cmp_eq_u32_e32 vcc, 0, v5
	s_and_saveexec_b64 s[0:1], vcc
	s_cbranch_execz .LBB0_226
	s_waitcnt lgkmcnt(0)
	v_add_f32_e32 v0, v0, v2
	v_fmamk_f32 v0, v0, 0x3b800000, v190
	v_mul_f32_e32 v2, 0x4b800000, v0
	v_cmp_gt_f32_e32 vcc, s3, v0
	s_nop 1
	v_cndmask_b32_e32 v0, v0, v2, vcc
	v_rsq_f32_e32 v0, v0
	s_nop 0
	v_mul_f32_e32 v2, 0x45800000, v0
	v_cndmask_b32_e32 v0, v0, v2, vcc
	v_mov_b32_e32 v2, 0x10000
	v_lshl_add_u32 v2, v4, 2, v2
	ds_write_b32 v2, v0
